# hyena sample e-loop: 2-stage software pipelining of LDS fragment reads, zero-row instead of cndmask
# speedup vs baseline: 1.0017x; 1.0017x over previous
.LBB0_721:
	v_mov_b32_e32 v0, 0
	s_xor_b64 s[12:13], s[88:89], -1
	s_movk_i32 s0, 0x3f80
	v_mov_b32_e32 v61, v78
	v_mov_b32_e32 v1, v0
	v_mov_b32_e32 v2, v0
	v_mov_b32_e32 v3, v0
	v_mov_b32_e32 v4, v0
	v_mov_b32_e32 v5, v0
	v_mov_b32_e32 v6, v0
	v_mov_b32_e32 v7, v0
	v_mov_b32_e32 v8, v0
	v_mov_b32_e32 v9, v0
	v_mov_b32_e32 v10, v0
	v_mov_b32_e32 v11, v0
	v_mov_b32_e32 v12, v0
	v_mov_b32_e32 v13, v0
	v_mov_b32_e32 v14, v0
	v_mov_b32_e32 v15, v0
	v_mov_b32_e32 v214, 0x24a00
	v_and_b32_e32 v162, 7, v192
	v_lshl_add_u32 v162, v162, 4, v214
	ds_write_b128 v162, v[0:3]
	s_waitcnt lgkmcnt(0)
	s_barrier
.LBB0_722:
	v_mov_b32_e32 v161, v78
	v_add_u32_e32 v126, 0x3f80, v77
	v_cmp_gt_u32_e32 vcc, 64, v161
	v_mad_u32_u24 v162, v161, s83, v65
	s_nop 0
	v_cndmask_b32_e32 v127, v214, v162, vcc
	ds_read_b128 v[128:131], v126
	ds_read_b128 v[144:147], v127
	ds_read_b128 v[132:135], v126 offset:32
	ds_read_b128 v[148:151], v127 offset:32
	ds_read_b128 v[136:139], v126 offset:64
	ds_read_b128 v[152:155], v127 offset:64
	ds_read_b128 v[140:143], v126 offset:96
	ds_read_b128 v[156:159], v127 offset:96
	s_movk_i32 s0, 47
.Lhy_s_loop:
	v_add_u32_e32 v161, -1, v161
	v_add_u32_e32 v126, 0xffffff80, v126
	v_cmp_gt_u32_e32 vcc, 64, v161
	v_mad_u32_u24 v162, v161, s83, v65
	s_nop 0
	v_cndmask_b32_e32 v160, v214, v162, vcc
	ds_read_b128 v[216:219], v126
	ds_read_b128 v[232:235], v160
	ds_read_b128 v[220:223], v126 offset:32
	ds_read_b128 v[236:239], v160 offset:32
	ds_read_b128 v[224:227], v126 offset:64
	ds_read_b128 v[240:243], v160 offset:64
	ds_read_b128 v[228:231], v126 offset:96
	ds_read_b128 v[244:247], v160 offset:96
	s_waitcnt lgkmcnt(8)
	v_mfma_f32_32x32x16_bf16 v[0:15], v[128:131], v[144:147], v[0:15]
	v_mfma_f32_32x32x16_bf16 v[0:15], v[132:135], v[148:151], v[0:15]
	v_mfma_f32_32x32x16_bf16 v[0:15], v[136:139], v[152:155], v[0:15]
	v_mfma_f32_32x32x16_bf16 v[0:15], v[140:143], v[156:159], v[0:15]
	v_add_u32_e32 v161, -1, v161
	v_add_u32_e32 v126, 0xffffff80, v126
	v_cmp_gt_u32_e32 vcc, 64, v161
	v_mad_u32_u24 v162, v161, s83, v65
	s_nop 0
	v_cndmask_b32_e32 v127, v214, v162, vcc
	ds_read_b128 v[128:131], v126
	ds_read_b128 v[144:147], v127
	ds_read_b128 v[132:135], v126 offset:32
	ds_read_b128 v[148:151], v127 offset:32
	ds_read_b128 v[136:139], v126 offset:64
	ds_read_b128 v[152:155], v127 offset:64
	ds_read_b128 v[140:143], v126 offset:96
	ds_read_b128 v[156:159], v127 offset:96
	s_waitcnt lgkmcnt(8)
	v_mfma_f32_32x32x16_bf16 v[0:15], v[216:219], v[232:235], v[0:15]
	v_mfma_f32_32x32x16_bf16 v[0:15], v[220:223], v[236:239], v[0:15]
	v_mfma_f32_32x32x16_bf16 v[0:15], v[224:227], v[240:243], v[0:15]
	v_mfma_f32_32x32x16_bf16 v[0:15], v[228:231], v[244:247], v[0:15]
	s_add_i32 s0, s0, -1
	s_cmp_lg_u32 s0, 0
	s_cbranch_scc1 .Lhy_s_loop
	s_waitcnt lgkmcnt(0)
	v_mfma_f32_32x32x16_bf16 v[0:15], v[128:131], v[144:147], v[0:15]
	v_mfma_f32_32x32x16_bf16 v[0:15], v[132:135], v[148:151], v[0:15]
	v_mfma_f32_32x32x16_bf16 v[0:15], v[136:139], v[152:155], v[0:15]
	v_mfma_f32_32x32x16_bf16 v[0:15], v[140:143], v[156:159], v[0:15]
	s_and_b64 s[0:1], s[88:89], exec
	s_cselect_b32 s0, s90, s82
	s_lshl_b32 s0, s0, 1
	s_add_u32 s0, s48, s0
	s_addc_u32 s1, s49, 0
	v_lshl_add_u64 v[96:97], v[22:23], 1, s[0:1]
	v_mov_b32_e32 v61, v112
	v_lshl_add_u64 v[96:97], v[96:97], 0, v[60:61]
	v_mov_b32_e32 v63, v112
	v_lshl_add_u64 v[96:97], v[96:97], 0, v[62:63]
	s_mov_b64 s[0:1], 0x4000
	v_lshl_add_u64 v[98:99], v[96:97], 0, s[0:1]
	s_movk_i32 s0, 0x4000
	v_add_co_u32_e32 v96, vcc, s0, v96
	s_nop 1
	v_addc_co_u32_e32 v97, vcc, 0, v97, vcc
	s_barrier
	global_load_dwordx2 v[96:97], v[96:97], off
	s_movk_i32 s0, 0x400
	s_mov_b64 s[88:89], 0
	s_and_b64 vcc, exec, s[12:13]
	s_waitcnt vmcnt(0)
	v_lshlrev_b32_e32 v100, 16, v96
	v_and_b32_e32 v101, 0xffff0000, v96
	v_lshlrev_b32_e32 v96, 16, v97
	v_and_b32_e32 v97, 0xffff0000, v97
	v_pk_mul_f32 v[0:1], v[0:1], v[100:101]
	v_pk_mul_f32 v[2:3], v[2:3], v[96:97]
	v_cvt_pk_bf16_f32 v0, v0, v1
	v_cvt_pk_bf16_f32 v1, v2, v3
	global_load_dwordx2 v[2:3], v[98:99], off offset:16
	s_waitcnt vmcnt(0)
	v_lshlrev_b32_e32 v96, 16, v2
	v_and_b32_e32 v97, 0xffff0000, v2
	v_pk_mul_f32 v[4:5], v[4:5], v[96:97]
	s_nop 0
	v_cvt_pk_bf16_f32 v2, v4, v5
	v_lshlrev_b32_e32 v4, 16, v3
	v_and_b32_e32 v5, 0xffff0000, v3
	v_pk_mul_f32 v[4:5], v[6:7], v[4:5]
	s_nop 0
	v_cvt_pk_bf16_f32 v3, v4, v5
	ds_write2_b64 v76, v[0:1], v[2:3] offset1:2
	global_load_dwordx2 v[0:1], v[98:99], off offset:32
	s_waitcnt vmcnt(0)
	v_lshlrev_b32_e32 v2, 16, v0
	v_and_b32_e32 v3, 0xffff0000, v0
	v_pk_mul_f32 v[2:3], v[8:9], v[2:3]
	s_nop 0
	v_cvt_pk_bf16_f32 v0, v2, v3
	v_lshlrev_b32_e32 v2, 16, v1
	v_and_b32_e32 v3, 0xffff0000, v1
	v_pk_mul_f32 v[2:3], v[10:11], v[2:3]
	s_nop 0
	v_cvt_pk_bf16_f32 v1, v2, v3
	global_load_dwordx2 v[2:3], v[98:99], off offset:48
	s_waitcnt vmcnt(0)
	v_lshlrev_b32_e32 v4, 16, v2
	v_and_b32_e32 v5, 0xffff0000, v2
	v_pk_mul_f32 v[4:5], v[12:13], v[4:5]
	s_nop 0
	v_cvt_pk_bf16_f32 v2, v4, v5
	v_lshlrev_b32_e32 v4, 16, v3
	v_and_b32_e32 v5, 0xffff0000, v3
	v_pk_mul_f32 v[4:5], v[14:15], v[4:5]
	s_nop 0
	v_cvt_pk_bf16_f32 v3, v4, v5
	ds_write2_b64 v76, v[0:1], v[2:3] offset0:4 offset1:6
	s_waitcnt lgkmcnt(0)
	s_barrier
	s_cbranch_vccz .LBB0_565
	s_lshl_b32 s0, s90, 1
	v_readlane_b32 s2, v254, 39
	v_readlane_b32 s3, v254, 40
	s_add_u32 s0, s2, s0
	s_addc_u32 s1, s3, 0
	v_lshlrev_b32_e32 v0, 1, v16
	v_mov_b32_e32 v1, v112
	v_lshl_add_u64 v[0:1], s[0:1], 0, v[0:1]
	s_mov_b64 s[0:1], 0x4000
	v_lshl_add_u64 v[4:5], v[0:1], 0, s[0:1]
	v_add_u32_e32 v0, v17, v67
	ds_read_b128 v[0:3], v0
	v_lshl_add_u64 v[6:7], v[50:51], 1, v[4:5]
	s_mov_b32 s96, 0
	s_movk_i32 s71, 0x90
	v_lshl_add_u64 v[4:5], v[42:43], 1, v[4:5]
	s_waitcnt lgkmcnt(0)
	global_store_dwordx4 v[6:7], v[0:3], off
	v_readlane_b32 s88, v255, 25
	s_movk_i32 s97, 0x5eed
	v_add_u32_e32 v0, v17, v66
	ds_read_b128 v[0:3], v0
	v_readlane_b32 s38, v253, 1
	s_movk_i32 s74, 0x2400
	s_movk_i32 s64, 0x1fff
	v_readlane_b32 s89, v255, 26
	s_waitcnt lgkmcnt(0)
	global_store_dwordx4 v[4:5], v[0:3], off
	s_barrier
	v_readlane_b32 s39, v253, 2
	s_branch .LBB0_466
